# baseline (speedup 1.0000x reference)
; __global__ void __launch_bounds__(NTHREADS, 2) fwd_megakernel(Params p_arg) {
;     ...
;           const int h = kvh * 4 + g;
;           const size_t tokq = tok0 + qt * 16 + fr;
;           bf16x8 qf[2];
;           qf[0] = *(const bf16x8*)(ZQp + tokq * 512 + h * 64 + fq * 8);
;           qf[1] = *(const bf16x8*)(ZQp + tokq * 512 + h * 64 + 32 + fq * 8);
;           f32x4 S[18];
; #pragma unroll
;           for (int i = 0; i < 18; ++i) {
;             S[i] = f32x4{0.f, 0.f, 0.f, 0.f};
; #pragma unroll
;             for (int ks = 0; ks < 2; ++ks) {
;               bf16x8 kf = *(const bf16x8*)(Ks + ((kt0 + i) * 16 + fr) * 72 + ks * 32 + fq * 8);
;               S[i] = __builtin_amdgcn_mfma_f32_16x16x32_bf16(kf, qf[ks], S[i], 0, 0, 0);
;             }
;             if ((i % 3) == 2) __builtin_amdgcn_sched_barrier(0);
;           }
.Lq_go:
	v_mov_b32_e32 v2, v200
	v_mov_b32_e32 v3, v201
	v_mov_b32_e32 v4, v202
	v_mov_b32_e32 v5, v203
	v_mov_b32_e32 v156, v204
	v_mov_b32_e32 v157, v205
	v_mov_b32_e32 v158, v206
	v_mov_b32_e32 v159, v207
	v_lshl_add_u64 v[6:7], v[108:109], 0, s[24:25]
	global_load_dwordx4 v[200:203], v[6:7], off offset:64
	global_load_dwordx4 v[204:207], v[6:7], off offset:128
	ds_read_b128 v[6:9], v133
	ds_read_b128 v[10:13], v133 offset:64
	s_waitcnt lgkmcnt(1)
	v_mfma_f32_16x16x32_bf16 v[6:9], v[6:9], v[2:5], 0
	s_waitcnt lgkmcnt(0)
	v_mfma_f32_16x16x32_bf16 v[70:73], v[10:13], v[156:159], v[6:9]
	ds_read_b128 v[10:13], v134 offset:64
	s_nop 4
	ds_read_b128 v[6:9], v134
	s_waitcnt lgkmcnt(0)
	v_mfma_f32_16x16x32_bf16 v[6:9], v[6:9], v[2:5], 0
	v_mfma_f32_16x16x32_bf16 v[66:69], v[10:13], v[156:159], v[6:9]
	ds_read_b128 v[10:13], v135 offset:64
	s_nop 5
	ds_read_b128 v[6:9], v135
	s_waitcnt lgkmcnt(0)
	v_mfma_f32_16x16x32_bf16 v[6:9], v[6:9], v[2:5], 0
	v_mfma_f32_16x16x32_bf16 v[62:65], v[10:13], v[156:159], v[6:9]
	s_nop 6
	ds_read_b128 v[6:9], v136
	ds_read_b128 v[10:13], v136 offset:64
	ds_read_b128 v[14:17], v137
	ds_read_b128 v[18:21], v137 offset:64
	s_waitcnt lgkmcnt(3)
	v_mfma_f32_16x16x32_bf16 v[6:9], v[6:9], v[2:5], 0
	s_waitcnt lgkmcnt(2)
	v_mfma_f32_16x16x32_bf16 v[58:61], v[10:13], v[156:159], v[6:9]
	ds_read_b128 v[10:13], v138 offset:64
	s_nop 4
	ds_read_b128 v[6:9], v138
	s_waitcnt lgkmcnt(3)
	v_mfma_f32_16x16x32_bf16 v[14:17], v[14:17], v[2:5], 0
	s_waitcnt lgkmcnt(0)
	v_mfma_f32_16x16x32_bf16 v[6:9], v[6:9], v[2:5], 0
	v_mfma_f32_16x16x32_bf16 v[54:57], v[18:21], v[156:159], v[14:17]
	v_mfma_f32_16x16x32_bf16 v[50:53], v[10:13], v[156:159], v[6:9]
	s_nop 5
	ds_read_b128 v[6:9], v139
	ds_read_b128 v[10:13], v139 offset:64
	ds_read_b128 v[14:17], v140
	ds_read_b128 v[18:21], v140 offset:64
	s_waitcnt lgkmcnt(3)
	v_mfma_f32_16x16x32_bf16 v[6:9], v[6:9], v[2:5], 0
	s_waitcnt lgkmcnt(2)
	v_mfma_f32_16x16x32_bf16 v[46:49], v[10:13], v[156:159], v[6:9]
	ds_read_b128 v[10:13], v141 offset:64
	s_nop 4
	ds_read_b128 v[6:9], v141
	s_waitcnt lgkmcnt(3)
	v_mfma_f32_16x16x32_bf16 v[14:17], v[14:17], v[2:5], 0
	s_waitcnt lgkmcnt(0)
	v_mfma_f32_16x16x32_bf16 v[6:9], v[6:9], v[2:5], 0
	v_mfma_f32_16x16x32_bf16 v[42:45], v[18:21], v[156:159], v[14:17]
	v_mfma_f32_16x16x32_bf16 v[38:41], v[10:13], v[156:159], v[6:9]
	s_nop 5
	ds_read_b128 v[6:9], v142
	ds_read_b128 v[10:13], v142 offset:64
	ds_read_b128 v[14:17], v143
	ds_read_b128 v[18:21], v143 offset:64
	s_waitcnt lgkmcnt(3)
	v_mfma_f32_16x16x32_bf16 v[6:9], v[6:9], v[2:5], 0
	s_waitcnt lgkmcnt(2)
	v_mfma_f32_16x16x32_bf16 v[34:37], v[10:13], v[156:159], v[6:9]
	ds_read_b128 v[10:13], v144 offset:64
	s_nop 4
	ds_read_b128 v[6:9], v144
	s_waitcnt lgkmcnt(3)
	v_mfma_f32_16x16x32_bf16 v[14:17], v[14:17], v[2:5], 0
	s_waitcnt lgkmcnt(0)
	v_mfma_f32_16x16x32_bf16 v[6:9], v[6:9], v[2:5], 0
	v_mfma_f32_16x16x32_bf16 v[30:33], v[18:21], v[156:159], v[14:17]
	v_mfma_f32_16x16x32_bf16 v[26:29], v[10:13], v[156:159], v[6:9]
	s_nop 5
	ds_read_b128 v[6:9], v145
	ds_read_b128 v[10:13], v145 offset:64
	ds_read_b128 v[14:17], v146
	ds_read_b128 v[18:21], v146 offset:64
	s_waitcnt lgkmcnt(3)
	v_mfma_f32_16x16x32_bf16 v[6:9], v[6:9], v[2:5], 0
	s_waitcnt lgkmcnt(2)
	v_mfma_f32_16x16x32_bf16 v[22:25], v[10:13], v[156:159], v[6:9]
	ds_read_b128 v[10:13], v147 offset:64
	s_nop 4
	ds_read_b128 v[6:9], v147
	s_waitcnt lgkmcnt(3)
	v_mfma_f32_16x16x32_bf16 v[14:17], v[14:17], v[2:5], 0
	s_waitcnt lgkmcnt(0)
	v_mfma_f32_16x16x32_bf16 v[6:9], v[6:9], v[2:5], 0
	v_mfma_f32_16x16x32_bf16 v[18:21], v[18:21], v[156:159], v[14:17]
	v_mfma_f32_16x16x32_bf16 v[14:17], v[10:13], v[156:159], v[6:9]
	s_nop 5
	ds_read_b128 v[6:9], v148
	ds_read_b128 v[10:13], v148 offset:64
	s_waitcnt lgkmcnt(1)
	v_mfma_f32_16x16x32_bf16 v[6:9], v[6:9], v[2:5], 0
	ds_read_b128 v[180:183], v150 offset:64
	s_waitcnt lgkmcnt(1)
	v_mfma_f32_16x16x32_bf16 v[10:13], v[10:13], v[156:159], v[6:9]
	s_nop 4
	ds_read_b128 v[6:9], v150
	s_waitcnt lgkmcnt(0)
	v_mfma_f32_16x16x32_bf16 v[6:9], v[6:9], v[2:5], 0
	v_mfma_f32_16x16x32_bf16 v[6:9], v[180:183], v[156:159], v[6:9]
	ds_read_b128 v[180:183], v152
	s_waitcnt lgkmcnt(0)
	v_mfma_f32_16x16x32_bf16 v[2:5], v[180:183], v[2:5], 0
	ds_read_b128 v[180:183], v152 offset:64
	s_waitcnt lgkmcnt(0)
; __global__ void __launch_bounds__(NTHREADS, 2) fwd_megakernel(Params p_arg) {
;     ...
;           const float slope = exp2f(-(float)(h + 1));
;           const float sinkv = pk->attn_sink[(size_t)l * 8 + h];
;           float d0 = (float)(kt0 * 16 + fq * 4 - 128 - qi);
;           asm volatile("" : "+v"(d0));
;           const float lo2 = fmaxf(-128.f, klo - 128.f - (float)qi), hi2 = fminf(128.f, khi - 129.f - (float)qi);
;           float mx = sinkv;
; #pragma unroll
;           for (int i = 0; i < 18; ++i)
; #pragma unroll
;             for (int r = 0; r < 4; ++r) {
;               float t = d0 + (float)(i * 16 + r);
;               bool ok = (t >= lo2) && (t <= hi2);
;               float v = ok ? (S[i][r] - slope * fabsf(t)) : -1e30f;
;               S[i][r] = v; mx = fmaxf(mx, v);
;             }
	v_mfma_f32_16x16x32_bf16 v[2:5], v[180:183], v[156:159], v[2:5]
	v_cvt_f32_u32_e32 v0, s0
	s_mov_b32 s1, 0x42fc0000
	v_mov_b32_e32 v155, v112
	v_cmp_lt_f32_e32 vcc, s1, v0
	s_and_b64 s[14:15], vcc, exec
	s_nop 0
	v_cndmask_b32_e32 v101, 0, v178, vcc
	v_sub_f32_e32 v0, v101, v0
	v_exp_f32_e32 v0, v0
	s_cselect_b32 s1, 0xffffffc0, 0
	v_ldexp_f32 v101, v0, s1
	global_load_dword v0, v1, s[12:13]
	s_nop 0
	v_lshlrev_b32_e32 v245, 16, v208
	v_fma_f32 v70, -v101, v245, v70
	v_and_b32_e32 v246, 0xffff0000, v208
	v_fma_f32 v71, -v101, v246, v71
	v_lshlrev_b32_e32 v245, 16, v209
	v_fma_f32 v72, -v101, v245, v72
	v_and_b32_e32 v246, 0xffff0000, v209
	v_fma_f32 v73, -v101, v246, v73
	v_lshlrev_b32_e32 v245, 16, v210
	v_fma_f32 v66, -v101, v245, v66
	v_and_b32_e32 v246, 0xffff0000, v210
	v_fma_f32 v67, -v101, v246, v67
	v_lshlrev_b32_e32 v245, 16, v211
	v_fma_f32 v68, -v101, v245, v68
	v_and_b32_e32 v246, 0xffff0000, v211
	v_fma_f32 v69, -v101, v246, v69
	v_lshlrev_b32_e32 v245, 16, v212
	v_fma_f32 v62, -v101, v245, v62
	v_and_b32_e32 v246, 0xffff0000, v212
	v_fma_f32 v63, -v101, v246, v63
	v_lshlrev_b32_e32 v245, 16, v213
	v_fma_f32 v64, -v101, v245, v64
	v_and_b32_e32 v246, 0xffff0000, v213
	v_fma_f32 v65, -v101, v246, v65
	v_lshlrev_b32_e32 v245, 16, v214
	v_fma_f32 v58, -v101, v245, v58
	v_and_b32_e32 v246, 0xffff0000, v214
	v_fma_f32 v59, -v101, v246, v59
	v_lshlrev_b32_e32 v245, 16, v215
	v_fma_f32 v60, -v101, v245, v60
	v_and_b32_e32 v246, 0xffff0000, v215
	v_fma_f32 v61, -v101, v246, v61
	v_lshlrev_b32_e32 v245, 16, v216
	v_fma_f32 v54, -v101, v245, v54
	v_and_b32_e32 v246, 0xffff0000, v216
	v_fma_f32 v55, -v101, v246, v55
	v_lshlrev_b32_e32 v245, 16, v217
	v_fma_f32 v56, -v101, v245, v56
	v_and_b32_e32 v246, 0xffff0000, v217
	v_fma_f32 v57, -v101, v246, v57
	v_lshlrev_b32_e32 v245, 16, v218
	v_fma_f32 v50, -v101, v245, v50
	v_and_b32_e32 v246, 0xffff0000, v218
	v_fma_f32 v51, -v101, v246, v51
	v_lshlrev_b32_e32 v245, 16, v219
	v_fma_f32 v52, -v101, v245, v52
	v_and_b32_e32 v246, 0xffff0000, v219
	v_fma_f32 v53, -v101, v246, v53
	v_lshlrev_b32_e32 v245, 16, v220
	v_fma_f32 v46, -v101, v245, v46
	v_and_b32_e32 v246, 0xffff0000, v220
	v_fma_f32 v47, -v101, v246, v47
	v_lshlrev_b32_e32 v245, 16, v221
	v_fma_f32 v48, -v101, v245, v48
	v_and_b32_e32 v246, 0xffff0000, v221
	v_fma_f32 v49, -v101, v246, v49
	v_lshlrev_b32_e32 v245, 16, v222
	v_fma_f32 v42, -v101, v245, v42
	v_and_b32_e32 v246, 0xffff0000, v222
	v_fma_f32 v43, -v101, v246, v43
	v_lshlrev_b32_e32 v245, 16, v223
	v_fma_f32 v44, -v101, v245, v44
	v_and_b32_e32 v246, 0xffff0000, v223
	v_fma_f32 v45, -v101, v246, v45
	v_lshlrev_b32_e32 v245, 16, v224
	v_fma_f32 v38, -v101, v245, v38
	v_and_b32_e32 v246, 0xffff0000, v224
	v_fma_f32 v156, -v101, v246, v39
	v_lshlrev_b32_e32 v245, 16, v225
	v_fma_f32 v40, -v101, v245, v40
	v_and_b32_e32 v246, 0xffff0000, v225
	v_fma_f32 v157, -v101, v246, v41
	v_lshlrev_b32_e32 v245, 16, v226
	v_fma_f32 v34, -v101, v245, v34
	v_and_b32_e32 v246, 0xffff0000, v226
	v_fma_f32 v158, -v101, v246, v35
	v_lshlrev_b32_e32 v245, 16, v227
	v_fma_f32 v36, -v101, v245, v36
	v_and_b32_e32 v246, 0xffff0000, v227
	v_fma_f32 v159, -v101, v246, v37
	v_lshlrev_b32_e32 v245, 16, v228
	v_fma_f32 v30, -v101, v245, v30
	v_and_b32_e32 v246, 0xffff0000, v228
	v_fma_f32 v160, -v101, v246, v31
	v_lshlrev_b32_e32 v245, 16, v229
	v_fma_f32 v32, -v101, v245, v32
	v_and_b32_e32 v246, 0xffff0000, v229
	v_fma_f32 v161, -v101, v246, v33
	v_lshlrev_b32_e32 v245, 16, v230
	v_fma_f32 v26, -v101, v245, v26
	v_and_b32_e32 v246, 0xffff0000, v230
	v_fma_f32 v180, -v101, v246, v27
	v_lshlrev_b32_e32 v245, 16, v231
	v_fma_f32 v28, -v101, v245, v28
	v_and_b32_e32 v246, 0xffff0000, v231
	v_fma_f32 v181, -v101, v246, v29
	v_lshlrev_b32_e32 v245, 16, v232
	v_fma_f32 v22, -v101, v245, v22
	v_and_b32_e32 v246, 0xffff0000, v232
	v_fma_f32 v182, -v101, v246, v23
	v_lshlrev_b32_e32 v245, 16, v233
	v_fma_f32 v24, -v101, v245, v24
	v_and_b32_e32 v246, 0xffff0000, v233
	v_fma_f32 v183, -v101, v246, v25
	v_lshlrev_b32_e32 v245, 16, v234
	v_fma_f32 v18, -v101, v245, v18
	v_and_b32_e32 v246, 0xffff0000, v234
	v_fma_f32 v184, -v101, v246, v19
	v_lshlrev_b32_e32 v245, 16, v235
	v_fma_f32 v20, -v101, v245, v20
	v_and_b32_e32 v246, 0xffff0000, v235
	v_fma_f32 v186, -v101, v246, v21
	v_lshlrev_b32_e32 v245, 16, v236
	v_fma_f32 v185, -v101, v245, v14
	v_and_b32_e32 v246, 0xffff0000, v236
	v_fma_f32 v15, -v101, v246, v15
	v_lshlrev_b32_e32 v245, 16, v237
	v_fma_f32 v187, -v101, v245, v16
	v_and_b32_e32 v246, 0xffff0000, v237
	v_fma_f32 v189, -v101, v246, v17
	v_lshlrev_b32_e32 v245, 16, v238
	v_fma_f32 v188, -v101, v245, v10
	v_and_b32_e32 v246, 0xffff0000, v238
	v_fma_f32 v190, -v101, v246, v11
	v_lshlrev_b32_e32 v245, 16, v239
	v_fma_f32 v12, -v101, v245, v12
	v_and_b32_e32 v246, 0xffff0000, v239
	v_fma_f32 v192, -v101, v246, v13
	v_lshlrev_b32_e32 v245, 16, v240
	v_fma_f32 v191, -v101, v245, v6
	v_and_b32_e32 v246, 0xffff0000, v240
	v_fma_f32 v7, -v101, v246, v7
	v_lshlrev_b32_e32 v245, 16, v241
	v_fma_f32 v193, -v101, v245, v8
	v_and_b32_e32 v246, 0xffff0000, v241
	v_fma_f32 v195, -v101, v246, v9
	v_lshlrev_b32_e32 v245, 16, v242
	v_fma_f32 v194, -v101, v245, v2
	v_and_b32_e32 v246, 0xffff0000, v242
	v_fma_f32 v196, -v101, v246, v3
	v_lshlrev_b32_e32 v245, 16, v243
	v_fma_f32 v198, -v101, v245, v4
	v_and_b32_e32 v246, 0xffff0000, v243
	v_fma_f32 v199, -v101, v246, v5
	s_waitcnt vmcnt(0)
; __global__ void __launch_bounds__(NTHREADS, 2) fwd_megakernel(Params p_arg) {
;     ...
;           mx = fmaxf(mx, __shfl_xor(mx, 16)); mx = fmaxf(mx, __shfl_xor(mx, 32));
;           float sum = 0.f;
; #pragma unroll
;           for (int i = 0; i < 18; ++i)
; #pragma unroll
;             for (int r = 0; r < 4; ++r) { float pv = __expf(S[i][r] - mx); S[i][r] = pv; sum += pv; }
	v_max3_f32 v244, v0, v70, v71
	v_max3_f32 v244, v244, v72, v73
	v_max3_f32 v244, v244, v66, v67
	v_max3_f32 v244, v244, v68, v69
	v_max3_f32 v244, v244, v62, v63
	v_max3_f32 v244, v244, v64, v65
	v_max3_f32 v244, v244, v58, v59
	v_max3_f32 v244, v244, v60, v61
	v_max3_f32 v244, v244, v54, v55
	v_max3_f32 v244, v244, v56, v57
	v_max3_f32 v244, v244, v50, v51
	v_max3_f32 v244, v244, v52, v53
	v_max3_f32 v244, v244, v46, v47
	v_max3_f32 v244, v244, v48, v49
	v_max3_f32 v244, v244, v42, v43
	v_max3_f32 v244, v244, v44, v45
	v_max3_f32 v244, v244, v38, v156
	v_max3_f32 v244, v244, v40, v157
	v_max3_f32 v244, v244, v34, v158
	v_max3_f32 v244, v244, v36, v159
	v_max3_f32 v244, v244, v30, v160
	v_max3_f32 v244, v244, v32, v161
	v_max3_f32 v244, v244, v26, v180
	v_max3_f32 v244, v244, v28, v181
	v_max3_f32 v244, v244, v22, v182
	v_max3_f32 v244, v244, v24, v183
	v_max3_f32 v244, v244, v18, v184
	v_max3_f32 v244, v244, v20, v186
	v_max3_f32 v244, v244, v185, v15
	v_max3_f32 v244, v244, v187, v189
	v_max3_f32 v244, v244, v188, v190
	v_max3_f32 v244, v244, v12, v192
	v_max3_f32 v244, v244, v191, v7
	v_max3_f32 v244, v244, v193, v195
	v_cmp_lt_i32_e32 vcc, v169, v164
	v_max3_f32 v244, v244, v194, v196
	v_max3_f32 v2, v244, v198, v199
	v_mov_b32_e32 v3, v2
	s_nop 1
	v_permlane16_swap_b32_e32 v3, v2
	s_nop 0
	v_max_f32_e32 v3, v3, v3
	v_max_f32_e32 v2, v2, v3
	v_mov_b32_e32 v3, v2
	s_nop 1
	v_permlane32_swap_b32_e32 v3, v2
	s_nop 0
	v_max_f32_e32 v3, v3, v3
	v_max_f32_e32 v197, v2, v3
	v_sub_f32_e32 v3, v71, v197
	v_mul_f32_e32 v3, 0x3fb8aa3b, v3
	v_exp_f32_e32 v71, v3
	v_sub_f32_e32 v3, v72, v197
	v_mul_f32_e32 v3, 0x3fb8aa3b, v3
	v_exp_f32_e32 v72, v3
	v_sub_f32_e32 v3, v73, v197
	v_mul_f32_e32 v3, 0x3fb8aa3b, v3
	v_exp_f32_e32 v73, v3
	v_sub_f32_e32 v3, v66, v197
	v_mul_f32_e32 v3, 0x3fb8aa3b, v3
	v_exp_f32_e32 v66, v3
	v_sub_f32_e32 v3, v67, v197
	v_mul_f32_e32 v3, 0x3fb8aa3b, v3
	v_exp_f32_e32 v67, v3
	v_sub_f32_e32 v3, v68, v197
	v_mul_f32_e32 v3, 0x3fb8aa3b, v3
	v_exp_f32_e32 v68, v3
	v_sub_f32_e32 v3, v69, v197
	v_mul_f32_e32 v3, 0x3fb8aa3b, v3
	v_exp_f32_e32 v69, v3
	v_sub_f32_e32 v3, v62, v197
	v_mul_f32_e32 v3, 0x3fb8aa3b, v3
	v_exp_f32_e32 v62, v3
	v_sub_f32_e32 v3, v63, v197
	v_mul_f32_e32 v3, 0x3fb8aa3b, v3
	v_exp_f32_e32 v63, v3
	v_sub_f32_e32 v3, v64, v197
	v_mul_f32_e32 v3, 0x3fb8aa3b, v3
	v_exp_f32_e32 v64, v3
	v_sub_f32_e32 v3, v65, v197
	v_mul_f32_e32 v3, 0x3fb8aa3b, v3
	v_exp_f32_e32 v65, v3
	v_sub_f32_e32 v3, v58, v197
	v_mul_f32_e32 v3, 0x3fb8aa3b, v3
	v_exp_f32_e32 v58, v3
	v_sub_f32_e32 v3, v59, v197
	v_mul_f32_e32 v3, 0x3fb8aa3b, v3
	v_exp_f32_e32 v59, v3
	v_sub_f32_e32 v3, v60, v197
	v_mul_f32_e32 v3, 0x3fb8aa3b, v3
	v_exp_f32_e32 v60, v3
	v_sub_f32_e32 v3, v61, v197
	v_mul_f32_e32 v3, 0x3fb8aa3b, v3
	v_exp_f32_e32 v61, v3
	v_sub_f32_e32 v3, v54, v197
	v_mul_f32_e32 v3, 0x3fb8aa3b, v3
	v_exp_f32_e32 v35, v3
	v_sub_f32_e32 v3, v55, v197
	v_mul_f32_e32 v3, 0x3fb8aa3b, v3
	v_exp_f32_e32 v39, v3
	v_sub_f32_e32 v3, v56, v197
	v_mul_f32_e32 v3, 0x3fb8aa3b, v3
	v_exp_f32_e32 v54, v3
	v_sub_f32_e32 v3, v57, v197
	v_mul_f32_e32 v3, 0x3fb8aa3b, v3
	v_exp_f32_e32 v55, v3
	v_sub_f32_e32 v3, v50, v197
	v_mul_f32_e32 v3, 0x3fb8aa3b, v3
	v_exp_f32_e32 v50, v3
	v_sub_f32_e32 v3, v51, v197
	v_mul_f32_e32 v3, 0x3fb8aa3b, v3
	v_exp_f32_e32 v56, v3
	v_sub_f32_e32 v3, v52, v197
	v_mul_f32_e32 v3, 0x3fb8aa3b, v3
	v_exp_f32_e32 v57, v3
	v_sub_f32_e32 v3, v53, v197
	v_mul_f32_e32 v3, 0x3fb8aa3b, v3
	v_exp_f32_e32 v53, v3
	v_sub_f32_e32 v3, v46, v197
	v_mul_f32_e32 v3, 0x3fb8aa3b, v3
	v_exp_f32_e32 v27, v3
	v_sub_f32_e32 v3, v47, v197
	v_mul_f32_e32 v3, 0x3fb8aa3b, v3
	v_exp_f32_e32 v31, v3
	v_sub_f32_e32 v3, v48, v197
	v_mul_f32_e32 v3, 0x3fb8aa3b, v3
	v_exp_f32_e32 v37, v3
	v_sub_f32_e32 v3, v49, v197
	v_mul_f32_e32 v3, 0x3fb8aa3b, v3
	v_exp_f32_e32 v41, v3
	v_sub_f32_e32 v3, v42, v197
	v_mul_f32_e32 v3, 0x3fb8aa3b, v3
	v_exp_f32_e32 v46, v3
	v_sub_f32_e32 v3, v43, v197
	v_mul_f32_e32 v3, 0x3fb8aa3b, v3
	v_exp_f32_e32 v48, v3
	v_sub_f32_e32 v3, v44, v197
	v_mul_f32_e32 v3, 0x3fb8aa3b, v3
	v_exp_f32_e32 v51, v3
	v_sub_f32_e32 v3, v45, v197
	v_sub_f32_e32 v2, v70, v197
	v_mul_f32_e32 v3, 0x3fb8aa3b, v3
	v_mul_f32_e32 v2, 0x3fb8aa3b, v2
	v_exp_f32_e32 v52, v3
	v_sub_f32_e32 v3, v38, v197
	v_exp_f32_e32 v70, v2
	v_mul_f32_e32 v3, 0x3fb8aa3b, v3
	v_exp_f32_e32 v19, v3
	v_sub_f32_e32 v3, v156, v197
	v_mul_f32_e32 v3, 0x3fb8aa3b, v3
	v_exp_f32_e32 v23, v3
	v_sub_f32_e32 v3, v40, v197
	v_add_f32_e32 v2, 0, v70
	v_mul_f32_e32 v3, 0x3fb8aa3b, v3
	v_add_f32_e32 v2, v2, v71
	v_exp_f32_e32 v29, v3
	v_sub_f32_e32 v3, v157, v197
	v_add_f32_e32 v2, v2, v72
	v_mul_f32_e32 v3, 0x3fb8aa3b, v3
	v_add_f32_e32 v2, v2, v73
	v_exp_f32_e32 v33, v3
	v_sub_f32_e32 v3, v34, v197
	v_add_f32_e32 v2, v2, v66
	v_mul_f32_e32 v3, 0x3fb8aa3b, v3
	v_add_f32_e32 v2, v2, v67
	v_exp_f32_e32 v42, v3
	v_sub_f32_e32 v3, v158, v197
	v_add_f32_e32 v2, v2, v68
	v_mul_f32_e32 v3, 0x3fb8aa3b, v3
	v_add_f32_e32 v2, v2, v69
	v_exp_f32_e32 v44, v3
	v_sub_f32_e32 v3, v36, v197
	v_add_f32_e32 v2, v2, v62
	v_mul_f32_e32 v3, 0x3fb8aa3b, v3
	v_add_f32_e32 v2, v2, v63
	v_exp_f32_e32 v47, v3
	v_sub_f32_e32 v3, v159, v197
	v_add_f32_e32 v2, v2, v64
	v_mul_f32_e32 v3, 0x3fb8aa3b, v3
	v_add_f32_e32 v2, v2, v65
	v_exp_f32_e32 v49, v3
	v_sub_f32_e32 v3, v30, v197
	v_add_f32_e32 v2, v2, v58
	v_mul_f32_e32 v3, 0x3fb8aa3b, v3
	v_add_f32_e32 v2, v2, v59
	v_exp_f32_e32 v13, v3
	v_sub_f32_e32 v3, v160, v197
	v_add_f32_e32 v2, v2, v60
	v_mul_f32_e32 v3, 0x3fb8aa3b, v3
	v_add_f32_e32 v2, v2, v61
	v_exp_f32_e32 v16, v3
	v_sub_f32_e32 v3, v32, v197
	v_add_f32_e32 v2, v2, v35
	v_mul_f32_e32 v3, 0x3fb8aa3b, v3
; __device__ __forceinline__ float rcpf(float x) { return __builtin_amdgcn_rcpf(x); }
; __global__ void __launch_bounds__(NTHREADS, 2) fwd_megakernel(Params p_arg) {
;     ...
;             for (int r = 0; r < 4; ++r) { float pv = __expf(S[i][r] - mx); S[i][r] = pv; sum += pv; }
;           sum += __shfl_xor(sum, 16); sum += __shfl_xor(sum, 32);
;           const float inv = rcpf(sum + __expf(sinkv - mx));
;           f32x4 O[4];
; #pragma unroll
;           for (int dt = 0; dt < 4; ++dt) O[dt] = f32x4{0.f, 0.f, 0.f, 0.f};
; #pragma unroll
;           for (int pp = 0; pp < 9; ++pp) {
;             union { bf16x8 v; uint32_t u[4]; } pf;
;             pf.u[0] = pack2(S[2*pp][0], S[2*pp][1]); pf.u[1] = pack2(S[2*pp][2], S[2*pp][3]);
;             pf.u[2] = pack2(S[2*pp+1][0], S[2*pp+1][1]); pf.u[3] = pack2(S[2*pp+1][2], S[2*pp+1][3]);
; #pragma unroll
;             for (int dt = 0; dt < 4; ++dt) {
;               union { bf16x8 v; uint2 h2[2]; } vfr;
;               const u16* vb = VT + (dt * 16 + fr) * 392 + (kt0 + 2 * pp) * 16 + fq * 4;
;               vfr.h2[0] = *(const uint2*)(vb);
;               vfr.h2[1] = *(const uint2*)(vb + 16);
;               O[dt] = __builtin_amdgcn_mfma_f32_16x16x32_bf16(vfr.v, pf.v, O[dt], 0, 0, 0);
	v_add_f32_e32 v2, v2, v39
	v_exp_f32_e32 v21, v3
	v_sub_f32_e32 v3, v161, v197
	v_add_f32_e32 v2, v2, v54
	v_mul_f32_e32 v3, 0x3fb8aa3b, v3
	v_add_f32_e32 v2, v2, v55
	v_exp_f32_e32 v25, v3
	v_sub_f32_e32 v3, v26, v197
	v_add_f32_e32 v2, v2, v50
	v_mul_f32_e32 v3, 0x3fb8aa3b, v3
	v_add_f32_e32 v2, v2, v56
	v_exp_f32_e32 v34, v3
	v_sub_f32_e32 v3, v180, v197
	v_add_f32_e32 v2, v2, v57
	v_mul_f32_e32 v3, 0x3fb8aa3b, v3
	v_add_f32_e32 v2, v2, v53
	v_exp_f32_e32 v38, v3
	v_sub_f32_e32 v3, v28, v197
	v_add_f32_e32 v2, v2, v27
	v_mul_f32_e32 v3, 0x3fb8aa3b, v3
	v_add_f32_e32 v2, v2, v31
	v_exp_f32_e32 v43, v3
	v_sub_f32_e32 v3, v181, v197
	v_add_f32_e32 v2, v2, v37
	v_mul_f32_e32 v3, 0x3fb8aa3b, v3
	v_add_f32_e32 v2, v2, v41
	v_exp_f32_e32 v45, v3
	v_sub_f32_e32 v3, v22, v197
	v_add_f32_e32 v2, v2, v46
	v_mul_f32_e32 v3, 0x3fb8aa3b, v3
	v_add_f32_e32 v2, v2, v48
	v_exp_f32_e32 v8, v3
	v_sub_f32_e32 v3, v182, v197
	v_add_f32_e32 v2, v2, v51
	v_mul_f32_e32 v3, 0x3fb8aa3b, v3
	v_add_f32_e32 v2, v2, v52
	v_exp_f32_e32 v10, v3
	v_sub_f32_e32 v3, v24, v197
	v_add_f32_e32 v2, v2, v19
	v_mul_f32_e32 v3, 0x3fb8aa3b, v3
	v_add_f32_e32 v2, v2, v23
	v_exp_f32_e32 v14, v3
	v_sub_f32_e32 v3, v183, v197
	v_add_f32_e32 v2, v2, v29
	v_mul_f32_e32 v3, 0x3fb8aa3b, v3
	v_add_f32_e32 v2, v2, v33
	v_exp_f32_e32 v17, v3
	v_sub_f32_e32 v3, v18, v197
	v_add_f32_e32 v2, v2, v42
	v_mul_f32_e32 v3, 0x3fb8aa3b, v3
	v_add_f32_e32 v2, v2, v44
	v_exp_f32_e32 v26, v3
	v_sub_f32_e32 v3, v184, v197
	v_add_f32_e32 v2, v2, v47
	v_mul_f32_e32 v3, 0x3fb8aa3b, v3
	v_add_f32_e32 v2, v2, v49
	v_exp_f32_e32 v30, v3
	v_sub_f32_e32 v3, v20, v197
	v_add_f32_e32 v2, v2, v13
	v_mul_f32_e32 v3, 0x3fb8aa3b, v3
	v_add_f32_e32 v2, v2, v16
	v_exp_f32_e32 v36, v3
	v_sub_f32_e32 v3, v186, v197
	v_add_f32_e32 v2, v2, v21
	v_mul_f32_e32 v3, 0x3fb8aa3b, v3
	v_add_f32_e32 v2, v2, v25
	v_exp_f32_e32 v40, v3
	v_sub_f32_e32 v3, v185, v197
	v_add_f32_e32 v2, v2, v34
	v_mul_f32_e32 v3, 0x3fb8aa3b, v3
	v_add_f32_e32 v2, v2, v38
	v_exp_f32_e32 v4, v3
	v_sub_f32_e32 v3, v15, v197
	v_add_f32_e32 v2, v2, v43
	v_mul_f32_e32 v3, 0x3fb8aa3b, v3
	v_add_f32_e32 v2, v2, v45
	v_exp_f32_e32 v6, v3
	v_sub_f32_e32 v3, v187, v197
	v_add_f32_e32 v2, v2, v8
	v_mul_f32_e32 v3, 0x3fb8aa3b, v3
	v_add_f32_e32 v2, v2, v10
	v_exp_f32_e32 v9, v3
	v_sub_f32_e32 v3, v189, v197
	v_add_f32_e32 v2, v2, v14
	v_mul_f32_e32 v3, 0x3fb8aa3b, v3
	v_add_f32_e32 v2, v2, v17
	v_exp_f32_e32 v11, v3
	v_sub_f32_e32 v3, v188, v197
	v_add_f32_e32 v2, v2, v26
	v_mul_f32_e32 v3, 0x3fb8aa3b, v3
	v_add_f32_e32 v2, v2, v30
	v_exp_f32_e32 v18, v3
	v_sub_f32_e32 v3, v190, v197
	v_add_f32_e32 v2, v2, v36
	v_mul_f32_e32 v3, 0x3fb8aa3b, v3
	v_add_f32_e32 v2, v2, v40
	v_exp_f32_e32 v22, v3
	v_sub_f32_e32 v3, v12, v197
	v_add_f32_e32 v2, v2, v4
	v_mul_f32_e32 v3, 0x3fb8aa3b, v3
	v_add_f32_e32 v2, v2, v6
	v_exp_f32_e32 v28, v3
	v_sub_f32_e32 v3, v192, v197
	v_add_f32_e32 v2, v2, v9
	v_mul_f32_e32 v3, 0x3fb8aa3b, v3
	v_add_f32_e32 v2, v2, v11
	v_exp_f32_e32 v32, v3
	v_add_f32_e32 v2, v2, v18
	v_add_f32_e32 v2, v2, v22
	v_add_f32_e32 v2, v2, v28
	v_add_f32_e32 v3, v2, v32
	v_sub_f32_e32 v2, v191, v197
	v_mul_f32_e32 v2, 0x3fb8aa3b, v2
	v_exp_f32_e32 v2, v2
	v_sub_f32_e32 v0, v0, v197
	v_mul_f32_e32 v0, 0x3fb8aa3b, v0
	v_exp_f32_e32 v0, v0
	v_add_f32_e32 v5, v3, v2
	v_sub_f32_e32 v3, v7, v197
	v_mul_f32_e32 v3, 0x3fb8aa3b, v3
	v_exp_f32_e32 v3, v3
	v_cvt_pk_bf16_f32 v70, v70, v71
	v_cvt_pk_bf16_f32 v71, v72, v73
	v_cvt_pk_bf16_f32 v72, v66, v67
	v_add_f32_e32 v7, v5, v3
	v_sub_f32_e32 v5, v193, v197
	v_mul_f32_e32 v5, 0x3fb8aa3b, v5
	v_exp_f32_e32 v5, v5
	v_add_u32_e32 v66, v115, v114
	v_add_u32_e32 v66, 0xd800, v66
	v_cvt_pk_bf16_f32 v73, v68, v69
	v_add_f32_e32 v12, v7, v5
	v_sub_f32_e32 v7, v195, v197
	v_mul_f32_e32 v7, 0x3fb8aa3b, v7
	v_exp_f32_e32 v7, v7
	ds_read2_b64 v[66:69], v66 offset1:4
	s_waitcnt lgkmcnt(0)
	v_mfma_f32_16x16x32_bf16 v[66:69], v[66:69], v[70:73], 0
	v_add_f32_e32 v15, v12, v7
	v_sub_f32_e32 v12, v194, v197
	v_mul_f32_e32 v12, 0x3fb8aa3b, v12
	v_exp_f32_e32 v12, v12
	s_nop 0
	v_add_f32_e32 v20, v15, v12
	v_sub_f32_e32 v15, v196, v197
	v_mul_f32_e32 v15, 0x3fb8aa3b, v15
	v_exp_f32_e32 v15, v15
	s_nop 0
	v_add_f32_e32 v24, v20, v15
	v_sub_f32_e32 v20, v198, v197
	v_mul_f32_e32 v20, 0x3fb8aa3b, v20
	v_exp_f32_e32 v20, v20
	s_nop 0
	v_add_f32_e32 v151, v24, v20
	v_sub_f32_e32 v24, v199, v197
	v_mul_f32_e32 v24, 0x3fb8aa3b, v24
	v_exp_f32_e32 v24, v24
	s_nop 0
	v_add_f32_e32 v151, v151, v24
	v_mov_b32_e32 v101, v151
	s_nop 1
	v_permlane16_swap_b32_e32 v101, v151
	s_nop 0
	v_add_f32_e32 v101, v151, v101
	v_mov_b32_e32 v151, v101
	s_nop 1
	v_permlane32_swap_b32_e32 v151, v101
	s_nop 0
	v_add_f32_e32 v101, v101, v151
	v_add_f32_e32 v0, v0, v101
	v_add_u32_e32 v101, v115, v116
	v_add_u32_e32 v101, 0xd800, v101
	ds_read2_b64 v[156:159], v101 offset1:4
	v_add_u32_e32 v101, v115, v117
	v_add_u32_e32 v101, 0xd800, v101
	ds_read2_b64 v[180:183], v101 offset1:4
	v_add_u32_e32 v101, v115, v118
	v_add_u32_e32 v101, 0xd800, v101
	ds_read2_b64 v[184:187], v101 offset1:4
	s_waitcnt lgkmcnt(2)
	v_mfma_f32_16x16x32_bf16 v[156:159], v[156:159], v[70:73], 0
	s_waitcnt lgkmcnt(1)
	v_mfma_f32_16x16x32_bf16 v[180:183], v[180:183], v[70:73], 0
	s_waitcnt lgkmcnt(0)
	v_mfma_f32_16x16x32_bf16 v[70:73], v[184:187], v[70:73], 0
	v_cvt_pk_bf16_f32 v62, v62, v63
	v_cvt_pk_bf16_f32 v63, v64, v65
	v_cvt_pk_bf16_f32 v64, v58, v59
	v_add_u32_e32 v58, v119, v114
	v_add_u32_e32 v58, 0xd800, v58
	v_cvt_pk_bf16_f32 v65, v60, v61
	ds_read2_b64 v[58:61], v58 offset1:4
	v_add_u32_e32 v101, v119, v117
	v_add_u32_e32 v101, 0xd800, v101
	s_waitcnt lgkmcnt(0)
; __global__ void __launch_bounds__(NTHREADS, 2) fwd_megakernel(Params p_arg) {
;     ...
;           for (int pp = 0; pp < 9; ++pp) {
;             union { bf16x8 v; uint32_t u[4]; } pf;
;             pf.u[0] = pack2(S[2*pp][0], S[2*pp][1]); pf.u[1] = pack2(S[2*pp][2], S[2*pp][3]);
;             pf.u[2] = pack2(S[2*pp+1][0], S[2*pp+1][1]); pf.u[3] = pack2(S[2*pp+1][2], S[2*pp+1][3]);
; #pragma unroll
;             for (int dt = 0; dt < 4; ++dt) {
;               union { bf16x8 v; uint2 h2[2]; } vfr;
;               const u16* vb = VT + (dt * 16 + fr) * 392 + (kt0 + 2 * pp) * 16 + fq * 4;
;               vfr.h2[0] = *(const uint2*)(vb);
;               vfr.h2[1] = *(const uint2*)(vb + 16);
;               O[dt] = __builtin_amdgcn_mfma_f32_16x16x32_bf16(vfr.v, pf.v, O[dt], 0, 0, 0);
;             }
;             __builtin_amdgcn_sched_barrier(0);
;           }
	v_mfma_f32_16x16x32_bf16 v[58:61], v[58:61], v[62:65], v[66:69]
	s_nop 2
	v_add_u32_e32 v66, v119, v116
	v_add_u32_e32 v66, 0xd800, v66
	ds_read2_b64 v[66:69], v66 offset1:4
	s_waitcnt lgkmcnt(0)
	v_mfma_f32_16x16x32_bf16 v[66:69], v[66:69], v[62:65], v[156:159]
	s_nop 2
	ds_read2_b64 v[156:159], v101 offset1:4
	v_add_u32_e32 v101, v119, v118
	v_add_u32_e32 v101, 0xd800, v101
	s_waitcnt lgkmcnt(0)
	v_mfma_f32_16x16x32_bf16 v[156:159], v[156:159], v[62:65], v[180:183]
	s_nop 2
	ds_read2_b64 v[180:183], v101 offset1:4
	s_waitcnt lgkmcnt(0)
	v_mfma_f32_16x16x32_bf16 v[62:65], v[180:183], v[62:65], v[70:73]
	s_nop 2
	v_cvt_pk_bf16_f32 v70, v35, v39
	v_add_u32_e32 v35, v120, v114
	v_add_u32_e32 v35, 0xd800, v35
	v_cvt_pk_bf16_f32 v71, v54, v55
	v_cvt_pk_bf16_f32 v72, v50, v56
	v_cvt_pk_bf16_f32 v73, v57, v53
	ds_read2_b64 v[54:57], v35 offset1:4
	v_add_u32_e32 v35, v120, v116
	v_add_u32_e32 v35, 0xd800, v35
	s_waitcnt lgkmcnt(0)
	v_mfma_f32_16x16x32_bf16 v[54:57], v[54:57], v[70:73], v[58:61]
	s_nop 2
	ds_read2_b64 v[58:61], v35 offset1:4
	v_add_u32_e32 v35, v120, v117
	v_add_u32_e32 v35, 0xd800, v35
	s_waitcnt lgkmcnt(0)
	v_mfma_f32_16x16x32_bf16 v[58:61], v[58:61], v[70:73], v[66:69]
	s_nop 2
	ds_read2_b64 v[66:69], v35 offset1:4
	v_add_u32_e32 v35, v120, v118
	v_add_u32_e32 v35, 0xd800, v35
	s_waitcnt lgkmcnt(0)
	v_mfma_f32_16x16x32_bf16 v[66:69], v[66:69], v[70:73], v[156:159]
	s_nop 2
	ds_read2_b64 v[156:159], v35 offset1:4
	s_waitcnt lgkmcnt(0)
	v_mfma_f32_16x16x32_bf16 v[62:65], v[156:159], v[70:73], v[62:65]
	v_cvt_pk_bf16_f32 v70, v27, v31
	v_add_u32_e32 v27, v121, v114
	v_add_u32_e32 v27, 0xd800, v27
	v_cvt_pk_bf16_f32 v73, v51, v52
	ds_read2_b64 v[50:53], v27 offset1:4
	v_add_u32_e32 v27, v121, v116
	v_cvt_pk_bf16_f32 v71, v37, v41
	v_cvt_pk_bf16_f32 v72, v46, v48
	v_add_u32_e32 v27, 0xd800, v27
	s_waitcnt lgkmcnt(0)
	v_mfma_f32_16x16x32_bf16 v[50:53], v[50:53], v[70:73], v[54:57]
	s_nop 2
	ds_read2_b64 v[54:57], v27 offset1:4
	v_add_u32_e32 v27, v121, v117
	v_add_u32_e32 v27, 0xd800, v27
	s_waitcnt lgkmcnt(0)
	v_mfma_f32_16x16x32_bf16 v[54:57], v[54:57], v[70:73], v[58:61]
	s_nop 2
	ds_read2_b64 v[58:61], v27 offset1:4
	v_add_u32_e32 v27, v121, v118
	v_add_u32_e32 v27, 0xd800, v27
	s_waitcnt lgkmcnt(0)
	v_mfma_f32_16x16x32_bf16 v[58:61], v[58:61], v[70:73], v[66:69]
	s_nop 2
	ds_read2_b64 v[66:69], v27 offset1:4
	s_waitcnt lgkmcnt(0)
	v_mfma_f32_16x16x32_bf16 v[62:65], v[66:69], v[70:73], v[62:65]
	v_cvt_pk_bf16_f32 v66, v19, v23
	v_add_u32_e32 v19, v122, v114
	v_add_u32_e32 v19, 0xd800, v19
	v_cvt_pk_bf16_f32 v69, v47, v49
	ds_read2_b64 v[46:49], v19 offset1:4
	v_add_u32_e32 v19, v122, v116
	v_cvt_pk_bf16_f32 v67, v29, v33
	v_cvt_pk_bf16_f32 v68, v42, v44
	v_add_u32_e32 v19, 0xd800, v19
	s_waitcnt lgkmcnt(0)
	v_mfma_f32_16x16x32_bf16 v[46:49], v[46:49], v[66:69], v[50:53]
	s_nop 2
	ds_read2_b64 v[50:53], v19 offset1:4
	v_add_u32_e32 v19, v122, v117
	v_add_u32_e32 v19, 0xd800, v19
	s_waitcnt lgkmcnt(0)
	v_mfma_f32_16x16x32_bf16 v[50:53], v[50:53], v[66:69], v[54:57]
	s_nop 2
	ds_read2_b64 v[54:57], v19 offset1:4
	v_add_u32_e32 v19, v122, v118
	v_add_u32_e32 v19, 0xd800, v19
	s_waitcnt lgkmcnt(0)
	v_mfma_f32_16x16x32_bf16 v[54:57], v[54:57], v[66:69], v[58:61]
	s_nop 2
	ds_read2_b64 v[58:61], v19 offset1:4
	s_waitcnt lgkmcnt(0)
	v_mfma_f32_16x16x32_bf16 v[58:61], v[58:61], v[66:69], v[62:65]
	s_nop 2
	v_cvt_pk_bf16_f32 v62, v13, v16
	v_add_u32_e32 v13, v123, v114
	v_add_u32_e32 v13, 0xd800, v13
	v_cvt_pk_bf16_f32 v65, v43, v45
	ds_read2_b64 v[42:45], v13 offset1:4
	v_add_u32_e32 v13, v123, v116
	v_cvt_pk_bf16_f32 v63, v21, v25
	v_cvt_pk_bf16_f32 v64, v34, v38
	v_add_u32_e32 v13, 0xd800, v13
	s_waitcnt lgkmcnt(0)
	v_mfma_f32_16x16x32_bf16 v[42:45], v[42:45], v[62:65], v[46:49]
	s_nop 2
	ds_read2_b64 v[46:49], v13 offset1:4
	v_add_u32_e32 v13, v123, v117
	v_add_u32_e32 v13, 0xd800, v13
	s_waitcnt lgkmcnt(0)
	v_mfma_f32_16x16x32_bf16 v[46:49], v[46:49], v[62:65], v[50:53]
	s_nop 2
	ds_read2_b64 v[50:53], v13 offset1:4
	v_add_u32_e32 v13, v123, v118
	v_add_u32_e32 v13, 0xd800, v13
	s_waitcnt lgkmcnt(0)
	v_mfma_f32_16x16x32_bf16 v[50:53], v[50:53], v[62:65], v[54:57]
	s_nop 2
	ds_read2_b64 v[54:57], v13 offset1:4
	s_waitcnt lgkmcnt(0)
; __device__ __forceinline__ uint2 pack4(float a, float b, float c, float d) { return make_uint2(pack2(a, b), pack2(c, d)); }
; __device__ __forceinline__ float rcpf(float x) { return __builtin_amdgcn_rcpf(x); }
; __global__ void __launch_bounds__(NTHREADS, 2) fwd_megakernel(Params p_arg) {
;     ...
;           const float inv = rcpf(sum + __expf(sinkv - mx));
;           f32x4 O[4];
; #pragma unroll
;           for (int dt = 0; dt < 4; ++dt) O[dt] = f32x4{0.f, 0.f, 0.f, 0.f};
; #pragma unroll
;           for (int pp = 0; pp < 9; ++pp) {
;             union { bf16x8 v; uint32_t u[4]; } pf;
;             pf.u[0] = pack2(S[2*pp][0], S[2*pp][1]); pf.u[1] = pack2(S[2*pp][2], S[2*pp][3]);
;             pf.u[2] = pack2(S[2*pp+1][0], S[2*pp+1][1]); pf.u[3] = pack2(S[2*pp+1][2], S[2*pp+1][3]);
; #pragma unroll
;             for (int dt = 0; dt < 4; ++dt) {
;               union { bf16x8 v; uint2 h2[2]; } vfr;
;               const u16* vb = VT + (dt * 16 + fr) * 392 + (kt0 + 2 * pp) * 16 + fq * 4;
;               vfr.h2[0] = *(const uint2*)(vb);
;               vfr.h2[1] = *(const uint2*)(vb + 16);
;               O[dt] = __builtin_amdgcn_mfma_f32_16x16x32_bf16(vfr.v, pf.v, O[dt], 0, 0, 0);
;             }
;             __builtin_amdgcn_sched_barrier(0);
;           }
; #pragma unroll
;           for (int dp = 0; dp < 2; ++dp)
;             store_pair16(ABp + tokq * 1024 + 512 + h * 64 + dp * 32, fq,
;                          pack4(O[2*dp][0] * inv, O[2*dp][1] * inv, O[2*dp][2] * inv, O[2*dp][3] * inv),
;                          pack4(O[2*dp+1][0] * inv, O[2*dp+1][1] * inv, O[2*dp+1][2] * inv, O[2*dp+1][3] * inv));
;         }
;         __syncthreads();
;       }
;     ...
;     }
	v_mfma_f32_16x16x32_bf16 v[54:57], v[54:57], v[62:65], v[58:61]
	s_nop 2
	v_cvt_pk_bf16_f32 v58, v8, v10
	v_add_u32_e32 v8, v124, v114
	v_add_u32_e32 v8, 0xd800, v8
	v_cvt_pk_bf16_f32 v61, v36, v40
	ds_read2_b64 v[34:37], v8 offset1:4
	v_add_u32_e32 v8, v124, v116
	v_add_u32_e32 v8, 0xd800, v8
	ds_read2_b64 v[38:41], v8 offset1:4
	v_add_u32_e32 v8, v124, v117
	v_cvt_pk_bf16_f32 v59, v14, v17
	v_cvt_pk_bf16_f32 v60, v26, v30
	v_add_u32_e32 v8, 0xd800, v8
	s_waitcnt lgkmcnt(1)
	v_mfma_f32_16x16x32_bf16 v[34:37], v[34:37], v[58:61], v[42:45]
	s_nop 2
	ds_read2_b64 v[42:45], v8 offset1:4
	v_add_u32_e32 v8, v124, v118
	v_add_u32_e32 v8, 0xd800, v8
	s_waitcnt lgkmcnt(1)
	v_mfma_f32_16x16x32_bf16 v[38:41], v[38:41], v[58:61], v[46:49]
	s_nop 2
	ds_read2_b64 v[46:49], v8 offset1:4
	s_waitcnt lgkmcnt(1)
	v_mfma_f32_16x16x32_bf16 v[42:45], v[42:45], v[58:61], v[50:53]
	s_waitcnt lgkmcnt(0)
	v_mfma_f32_16x16x32_bf16 v[46:49], v[46:49], v[58:61], v[54:57]
	v_cvt_pk_bf16_f32 v8, v4, v6
	v_add_u32_e32 v4, v125, v114
	v_add_u32_e32 v4, 0xd800, v4
	v_cvt_pk_bf16_f32 v10, v18, v22
	ds_read2_b64 v[16:19], v4 offset1:4
	v_add_u32_e32 v4, v125, v116
	v_add_u32_e32 v4, 0xd800, v4
	v_cvt_pk_bf16_f32 v9, v9, v11
	v_cvt_pk_bf16_f32 v11, v28, v32
	ds_read2_b64 v[26:29], v4 offset1:4
	v_add_u32_e32 v4, v125, v117
	v_add_u32_e32 v4, 0xd800, v4
	ds_read2_b64 v[30:33], v4 offset1:4
	v_add_u32_e32 v4, v125, v118
	v_add_u32_e32 v4, 0xd800, v4
	s_waitcnt lgkmcnt(2)
	v_mfma_f32_16x16x32_bf16 v[16:19], v[16:19], v[8:11], v[34:37]
	s_nop 2
	ds_read2_b64 v[34:37], v4 offset1:4
	s_waitcnt lgkmcnt(2)
	v_mfma_f32_16x16x32_bf16 v[26:29], v[26:29], v[8:11], v[38:41]
	s_waitcnt lgkmcnt(1)
	v_mfma_f32_16x16x32_bf16 v[30:33], v[30:33], v[8:11], v[42:45]
	s_waitcnt lgkmcnt(0)
	v_mfma_f32_16x16x32_bf16 v[8:11], v[34:37], v[8:11], v[46:49]
	v_add_u32_e32 v6, v126, v114
	v_add_u32_e32 v6, 0xd800, v6
	v_cvt_pk_bf16_f32 v4, v12, v15
	ds_read2_b64 v[12:15], v6 offset1:4
	v_add_u32_e32 v6, v126, v116
	v_cvt_pk_bf16_f32 v2, v2, v3
	v_cvt_pk_bf16_f32 v3, v5, v7
	v_cvt_pk_bf16_f32 v5, v20, v24
	v_add_u32_e32 v6, 0xd800, v6
	s_waitcnt lgkmcnt(0)
	v_mfma_f32_16x16x32_bf16 v[12:15], v[12:15], v[2:5], v[16:19]
	s_nop 2
	ds_read2_b64 v[16:19], v6 offset1:4
	v_add_u32_e32 v6, v126, v117
	v_add_u32_e32 v6, 0xd800, v6
	ds_read2_b64 v[20:23], v6 offset1:4
	v_add_u32_e32 v6, v126, v118
	v_add_u32_e32 v6, 0xd800, v6
	s_waitcnt lgkmcnt(1)
	v_mfma_f32_16x16x32_bf16 v[16:19], v[16:19], v[2:5], v[26:29]
	s_nop 2
	ds_read2_b64 v[24:27], v6 offset1:4
	s_waitcnt lgkmcnt(1)
	v_mfma_f32_16x16x32_bf16 v[20:23], v[20:23], v[2:5], v[30:33]
	s_waitcnt lgkmcnt(0)
	v_mfma_f32_16x16x32_bf16 v[2:5], v[24:27], v[2:5], v[8:11]
	v_rcp_f32_e32 v0, v0
	s_nop 1
	v_lshl_add_u64 v[10:11], v[110:111], 0, s[24:25]
	s_add_u32 s24, s24, 0x80
	s_addc_u32 s25, s25, 0
	s_add_i32 s0, s0, 1
	s_add_u32 s12, s12, 4
	v_pk_mul_f32 v[6:7], v[0:1], v[12:13] op_sel_hi:[0,1]
	v_pk_mul_f32 v[8:9], v[0:1], v[14:15] op_sel_hi:[0,1]
	v_pk_mul_f32 v[12:13], v[0:1], v[16:17] op_sel_hi:[0,1]
	v_pk_mul_f32 v[14:15], v[0:1], v[18:19] op_sel_hi:[0,1]
	s_addc_u32 s13, s13, 0
	v_pk_mul_f32 v[16:17], v[0:1], v[20:21] op_sel_hi:[0,1]
	v_pk_mul_f32 v[18:19], v[0:1], v[22:23] op_sel_hi:[0,1]
	v_pk_mul_f32 v[20:21], v[0:1], v[2:3] op_sel_hi:[0,1]
	v_pk_mul_f32 v[22:23], v[0:1], v[4:5] op_sel_hi:[0,1]
	v_cvt_pk_bf16_f32 v2, v6, v7
	v_cvt_pk_bf16_f32 v3, v8, v9
	v_cvt_pk_bf16_f32 v4, v12, v13
	v_cvt_pk_bf16_f32 v5, v14, v15
	s_cmpk_eq_i32 s24, 0x200
	v_cvt_pk_bf16_f32 v6, v16, v17
	v_cvt_pk_bf16_f32 v7, v18, v19
	v_cvt_pk_bf16_f32 v8, v20, v21
	v_cvt_pk_bf16_f32 v9, v22, v23
	v_permlane16_swap_b32_e32 v2, v4
	v_permlane16_swap_b32_e32 v3, v5
	v_permlane16_swap_b32_e32 v6, v8
	v_permlane16_swap_b32_e32 v7, v9
	global_store_dwordx4 v[10:11], v[2:5], off offset:-64
	global_store_dwordx4 v[10:11], v[6:9], off
	s_cbranch_scc0 .LBB0_312
	s_mov_b32 s28, 1
	s_mov_b64 s[12:13], 0
	s_and_b64 vcc, exec, s[92:93]
	s_barrier
	s_cbranch_vccz .LBB0_299
	s_add_i32 s99, s99, s3
	s_add_i32 s98, s98, s3
	s_cmpk_gt_i32 s99, 0xff
	s_cbranch_scc0 .LBB0_294
